# same file, second timing: barrier relocation at 7 GEMM sites (P0->G1 barrier kept whole) + static priority for waves 4-7 in the mixer units
# baseline (speedup 1.0000x reference)
; #define LAS __attribute__((address_space(3)))
; #define FRESH() int tid = threadIdx.x; asm volatile("" : "+v"(tid)); const int lane = tid & 63, wave = __builtin_amdgcn_readfirstlane(tid >> 6), gw = bx * 8 + wave, ngw = G * 8; (void)lane; (void)gw; (void)ngw
; __device__ __forceinline__ void p0_prologue(ArgsP A, unsigned char* lds, int gw, int ngw, int lane, int wave) {
;     float* scr = (float*)(lds + wave * 16384);
;     unsigned char* ws = A->ws;
;     constexpr int I_FF = 32 * 176, I_IN = 32 * 134, I_SQ = 32 * 64, I_UQ = 8 * 24, I_UKV = 2 * 32, I_GLU = 8 * 16, I_PP = 4 * 64;
;     constexpr int PER_L = 6 * I_FF + I_IN + 2 * I_SQ + I_UQ + I_UKV + I_GLU + I_PP;
;     for (int it = gw; it < DEPTH * PER_L; it += ngw) {
;         const int l = it / PER_L; int r = it % PER_L; unsigned char* wl = ws + WS_W + (size_t)l * WL_SIZE;
; template <int PHM, int MIXM>
; __global__ void __launch_bounds__(512, 2) mega(Args Aval) {
;     ...
;     const int lo = A->ph_lo, hi = A->ph_hi;
;     cg::grid_group grid = cg::this_grid();
;     __shared__ int s_item;
;     __shared__ unsigned s_bar[2];
;     if (threadIdx.x < 2) s_bar[threadIdx.x] = 0u;
;     __syncthreads();
;     XcdBarrier xbar; xbar.bar = (unsigned*)(ws + WS_CTL) + 2048; xbar.x = 0; xbar.st = nullptr;
;     if (hi - lo > 1) xbar = xcd_barrier_post((unsigned*)(ws + WS_CTL) + 2048, (volatile LAS unsigned*)s_bar);
;     ...
;     if (hi > (1 << 20)) grid.sync();
;     if ((PHM & 1) && IN(0)) { FRESH(); p0_prologue(A, lds, gw, ngw, lane, wave); if (PROBE_DUP & 8) { __syncthreads(); p0_prologue(A, lds, gw, ngw, lane, wave); } }
.LBB0_19:
	v_writelane_b32 v255, s74, 41
	v_writelane_b32 v255, s68, 42
	s_mov_b32 s100, 0
	s_nop 0
	v_writelane_b32 v255, s100, 40
.Lprobe_reenter:
	v_readlane_b32 s4, v252, 0
	v_readlane_b32 s5, v252, 1
	s_nop 1
	v_writelane_b32 v252, s28, 5
	s_waitcnt lgkmcnt(0)
	s_cmp_lt_i32 s4, 1
	s_cselect_b64 s[2:3], -1, 0
	s_cmp_gt_i32 s5, 0
	s_cselect_b64 s[4:5], -1, 0
	v_writelane_b32 v252, s29, 6
	s_and_b64 s[16:17], s[2:3], s[4:5]
	v_writelane_b32 v252, s30, 7
	s_andn2_b64 vcc, exec, s[16:17]
	v_writelane_b32 v252, s31, 8
	s_cbranch_vccnz .LBB0_150
	v_mov_b32_e32 v92, v238
	s_lshl_b32 s71, s74, 3
	v_readfirstlane_b32 s2, v92
	s_ashr_i32 s70, s2, 6
	s_lshl_b32 s2, s70, 14
	s_add_i32 s69, s70, s71
	s_lshl_b32 s20, s76, 3
	s_add_i32 s21, s2, 16
	s_cmp_gt_i32 s69, 0x14e7f
	v_and_b32_e32 v93, 63, v92
	s_cbranch_scc1 .LBB0_109
	s_load_dwordx4 s[4:7], s[18:19], 0x140
	v_lshlrev_b32_e32 v0, 2, v93
	v_lshrrev_b32_e32 v16, 3, v93
	v_and_b32_e32 v0, 28, v0
	v_lshlrev_b32_e32 v2, 3, v93
	s_waitcnt lgkmcnt(0)
	s_add_u32 s38, s6, 0x10000
	v_lshl_add_u32 v1, v0, 2, s21
	v_mul_u32_u24_e32 v3, 0x84, v16
	v_and_b32_e32 v2, 56, v2
	s_addc_u32 s39, s7, 0
	v_mul_u32_u24_e32 v4, 0x84, v2
	v_lshlrev_b32_e32 v5, 2, v16
	s_lshl_b32 s2, s69, 2
	v_add_u32_e32 v25, v1, v3
	v_mov_b32_e32 v9, 0
	v_or_b32_e32 v17, 8, v16
	v_or_b32_e32 v18, 16, v16
	v_or_b32_e32 v19, 24, v16
	v_or_b32_e32 v20, 32, v16
	v_or_b32_e32 v21, 40, v16
	v_or_b32_e32 v22, 48, v16
	v_or_b32_e32 v23, 56, v16
	v_add3_u32 v24, s21, v4, v5
	s_lshl_b32 s40, s69, 5
	s_lshl_b32 s41, s20, 5
	s_add_i32 s42, s2, 0x100
	s_lshl_b32 s43, s20, 2
	v_add_u32_e32 v26, 0x420, v25
	v_add_u32_e32 v27, 0x428, v25
	v_add_u32_e32 v28, 0x840, v25
	v_add_u32_e32 v29, 0x848, v25
	v_add_u32_e32 v30, 0xc60, v25
	v_add_u32_e32 v31, 0xc68, v25
	v_add_u32_e32 v32, 0x1080, v25
	v_add_u32_e32 v33, 0x1088, v25
	v_add_u32_e32 v34, 0x14a0, v25
	v_add_u32_e32 v35, 0x14a8, v25
	v_add_u32_e32 v36, 0x18c0, v25
	v_add_u32_e32 v37, 0x18c8, v25
	v_add_u32_e32 v38, 0x1ce0, v25
	v_add_u32_e32 v39, 0x1ce8, v25
	s_mov_b64 s[4:5], 0xa6c0000
	s_mov_b64 s[6:7], 0xa640000
	s_mov_b64 s[8:9], 0xa5c0000
	s_movk_i32 s44, 0xc00
	s_mov_b64 s[10:11], 0xa500000
	s_mov_b64 s[12:13], 0x8f00000
	s_movk_i32 s45, 0x1600
	s_mov_b64 s[14:15], 0x5b00000
	s_mov_b64 s[22:23], 0x5300000
	s_mov_b64 s[24:25], 0x4200000
	s_mov_b64 s[26:27], 0x2c00000
	v_lshlrev_b32_e32 v10, 2, v0
	v_lshlrev_b32_e32 v12, 1, v2
	s_mov_b32 s46, s69
	s_branch .LBB0_23

; #define PG8_STAGE(bufoff, gbase, voff) do { _Pragma("unroll") for (int _i = 0; _i < 2; ++_i) \
;         __builtin_amdgcn_global_load_lds((const unsigned*)((const char*)(gbase) + (voff)[_i]), (LAS unsigned*)(lds + (bufoff) + ldsw + _i * 8192), 16, 0, 0); } while (0)
; #define PG8_WAIT_V(n) asm volatile("s_waitcnt vmcnt(" #n ")" ::: "memory")
; #define PG8_BAR __builtin_amdgcn_s_barrier()
; template <class Epi, bool ALIGN_EPI = PG8_ALIGN>
; __device__ __forceinline__ void gemm_phase(LAS unsigned char* lds, const Gemm g, const StaticOrder& S, const Epi& E) {
;     ...
;     f32x4 acc[2][2][4][2];
; #pragma unroll
;     for (int a = 0; a < 2; ++a)
; #pragma unroll
;         for (int b = 0; b < 2; ++b)
; #pragma unroll
;             for (int m = 0; m < 4; ++m)
; #pragma unroll
;                 for (int n = 0; n < 2; ++n) acc[a][b][m][n] = (f32x4){0.f, 0.f, 0.f, 0.f};
;     bf16x8 At[4][2], B0[2][2], B1[2][2];
;     const char* cA = (const char*)g.A + (size_t)cur.pm * tstepA; const char* cB = (const char*)g.Bt + (size_t)cur.pn * tstepB;
;     PG8_STAGE(PG8_SB(0, 0), cB, voffB); PG8_STAGE(PG8_SB(0, 1), cB + hstepB, voffB); PG8_STAGE(PG8_SA(0, 0), cA, voffA); PG8_STAGE(PG8_SA(0, 1), cA + hstepA, voffA);
;     if (wr == 1) PG8_BAR;
;     PG8_WAIT_V(2); PG8_BAR;
;     PG8_STAGE(PG8_SB(1, 0), cB + kstep, voffB); PG8_STAGE(PG8_SA(1, 0), cA + kstep, voffA); PG8_STAGE(PG8_SB(1, 1), cB + hstepB + kstep, voffB);
;     PG8_WAIT_V(6); PG8_BAR;
;     for (;;) {
;         const bool has_next = S.next(ui + 1, nxt);
;         const char* nA = has_next ? (const char*)g.A + (size_t)nxt.pm * tstepA : cA; const char* nB = has_next ? (const char*)g.Bt + (size_t)nxt.pn * tstepB : cB;
;     ...
; #pragma unroll
;         for (int a = 0; a < 2; ++a)
; #pragma unroll
;             for (int b = 0; b < 2; ++b)
; #pragma unroll
;                 for (int m = 0; m < 4; ++m)
; #pragma unroll
;                     for (int n = 0; n < 2; ++n) acc[a][b][m][n] = (f32x4){0.f, 0.f, 0.f, 0.f};
;         cur = nxt; cA = nA; cB = nB; ++ui;
.LBB0_217:
	s_ashr_i32 s15, s14, 31
	s_lshl_b64 s[40:41], s[14:15], 20
	s_add_u32 s40, s58, s40
	v_mov_b32_e32 v127, 0
	s_addc_u32 s41, s59, s41
	s_andn2_b64 vcc, exec, s[10:11]
	v_mov_b32_e32 v126, v127
	v_mov_b32_e32 v125, v127
	v_mov_b32_e32 v124, v127
	v_mov_b32_e32 v119, v127
	v_mov_b32_e32 v118, v127
	v_mov_b32_e32 v117, v127
	v_mov_b32_e32 v116, v127
	v_mov_b32_e32 v111, v127
	v_mov_b32_e32 v110, v127
	v_mov_b32_e32 v109, v127
	v_mov_b32_e32 v108, v127
	v_mov_b32_e32 v103, v127
	v_mov_b32_e32 v102, v127
	v_mov_b32_e32 v101, v127
	v_mov_b32_e32 v100, v127
	v_mov_b32_e32 v95, v127
	v_mov_b32_e32 v94, v127
	v_mov_b32_e32 v93, v127
	v_mov_b32_e32 v92, v127
	v_mov_b32_e32 v87, v127
	v_mov_b32_e32 v86, v127
	v_mov_b32_e32 v85, v127
	v_mov_b32_e32 v84, v127
	v_mov_b32_e32 v79, v127
	v_mov_b32_e32 v78, v127
	v_mov_b32_e32 v77, v127
	v_mov_b32_e32 v76, v127
	v_mov_b32_e32 v71, v127
	v_mov_b32_e32 v70, v127
	v_mov_b32_e32 v69, v127
	v_mov_b32_e32 v68, v127
	v_mov_b32_e32 v123, v127
	v_mov_b32_e32 v122, v127
	v_mov_b32_e32 v121, v127
	v_mov_b32_e32 v120, v127
	v_mov_b32_e32 v115, v127
	v_mov_b32_e32 v114, v127
	v_mov_b32_e32 v113, v127
	v_mov_b32_e32 v112, v127
	v_mov_b32_e32 v107, v127
	v_mov_b32_e32 v106, v127
	v_mov_b32_e32 v105, v127
	v_mov_b32_e32 v104, v127
	v_mov_b32_e32 v99, v127
	v_mov_b32_e32 v98, v127
	v_mov_b32_e32 v97, v127
	v_mov_b32_e32 v96, v127
	v_mov_b32_e32 v91, v127
	v_mov_b32_e32 v90, v127
	v_mov_b32_e32 v89, v127
	v_mov_b32_e32 v88, v127
	v_mov_b32_e32 v83, v127
	v_mov_b32_e32 v82, v127
	v_mov_b32_e32 v81, v127
	v_mov_b32_e32 v80, v127
	v_mov_b32_e32 v75, v127
	v_mov_b32_e32 v74, v127
	v_mov_b32_e32 v73, v127
	v_mov_b32_e32 v72, v127
	v_mov_b32_e32 v67, v127
	v_mov_b32_e32 v66, v127
	v_mov_b32_e32 v65, v127
	v_mov_b32_e32 v64, v127
	v_mov_b32_e32 v63, v127
	v_mov_b32_e32 v62, v127
	v_mov_b32_e32 v61, v127
	v_mov_b32_e32 v60, v127
	v_mov_b32_e32 v55, v127
	v_mov_b32_e32 v54, v127
	v_mov_b32_e32 v53, v127
	v_mov_b32_e32 v52, v127
	v_mov_b32_e32 v47, v127
	v_mov_b32_e32 v46, v127
	v_mov_b32_e32 v45, v127
	v_mov_b32_e32 v44, v127
	v_mov_b32_e32 v39, v127
	v_mov_b32_e32 v38, v127
	v_mov_b32_e32 v37, v127
	v_mov_b32_e32 v36, v127
	v_mov_b32_e32 v31, v127
	v_mov_b32_e32 v30, v127
	v_mov_b32_e32 v29, v127
	v_mov_b32_e32 v28, v127
	v_mov_b32_e32 v23, v127
	v_mov_b32_e32 v22, v127
	v_mov_b32_e32 v21, v127
	v_mov_b32_e32 v20, v127
	v_mov_b32_e32 v15, v127
	v_mov_b32_e32 v14, v127
	v_mov_b32_e32 v13, v127
	v_mov_b32_e32 v12, v127
	v_mov_b32_e32 v7, v127
	v_mov_b32_e32 v6, v127
	v_mov_b32_e32 v5, v127
	v_mov_b32_e32 v4, v127
	v_mov_b32_e32 v59, v127
	v_mov_b32_e32 v58, v127
	v_mov_b32_e32 v57, v127
	v_mov_b32_e32 v56, v127
	v_mov_b32_e32 v51, v127
	v_mov_b32_e32 v50, v127
	v_mov_b32_e32 v49, v127
	v_mov_b32_e32 v48, v127
	v_mov_b32_e32 v43, v127
	v_mov_b32_e32 v42, v127
	v_mov_b32_e32 v41, v127
	v_mov_b32_e32 v40, v127
	v_mov_b32_e32 v35, v127
	v_mov_b32_e32 v34, v127
	v_mov_b32_e32 v33, v127
	v_mov_b32_e32 v32, v127
	v_mov_b32_e32 v27, v127
	v_mov_b32_e32 v26, v127
	v_mov_b32_e32 v25, v127
	v_mov_b32_e32 v24, v127
	v_mov_b32_e32 v19, v127
	v_mov_b32_e32 v18, v127
	v_mov_b32_e32 v17, v127
	v_mov_b32_e32 v16, v127
	v_mov_b32_e32 v11, v127
	v_mov_b32_e32 v10, v127
	v_mov_b32_e32 v9, v127
	v_mov_b32_e32 v8, v127
	v_mov_b32_e32 v3, v127
	v_mov_b32_e32 v2, v127
	v_mov_b32_e32 v1, v127
	v_mov_b32_e32 v0, v127
	s_cbranch_vccnz .LBB0_220
	s_and_b64 s[2:3], s[2:3], exec
	s_cselect_b32 s15, s41, s37
	s_cselect_b32 s34, s40, s36
	s_add_u32 s2, s36, 0x80080
	s_addc_u32 s3, s37, 0
	s_add_u32 s36, s24, 0x100
	v_mov_b32_e32 v0, 0
	s_addc_u32 s37, s25, 0
	s_mov_b32 s24, 0
	v_mov_b32_e32 v1, v0
	v_mov_b32_e32 v2, v0
	v_mov_b32_e32 v3, v0
	v_mov_b32_e32 v8, v0
	v_mov_b32_e32 v9, v0
	v_mov_b32_e32 v10, v0
	v_mov_b32_e32 v11, v0
	v_mov_b32_e32 v16, v0
	v_mov_b32_e32 v17, v0
	v_mov_b32_e32 v18, v0
	v_mov_b32_e32 v19, v0
	v_mov_b32_e32 v24, v0
	v_mov_b32_e32 v25, v0
	v_mov_b32_e32 v26, v0
	v_mov_b32_e32 v27, v0
	v_mov_b32_e32 v32, v0
	v_mov_b32_e32 v33, v0
	v_mov_b32_e32 v34, v0
	v_mov_b32_e32 v35, v0
	v_mov_b32_e32 v40, v0
	v_mov_b32_e32 v41, v0
	v_mov_b32_e32 v42, v0
	v_mov_b32_e32 v43, v0
	v_mov_b32_e32 v48, v0
	v_mov_b32_e32 v49, v0
	v_mov_b32_e32 v50, v0
	v_mov_b32_e32 v51, v0
	v_mov_b32_e32 v56, v0
	v_mov_b32_e32 v57, v0
	v_mov_b32_e32 v58, v0
	v_mov_b32_e32 v59, v0
	v_mov_b32_e32 v4, v0
	v_mov_b32_e32 v5, v0
	v_mov_b32_e32 v6, v0
	v_mov_b32_e32 v7, v0
	v_mov_b32_e32 v12, v0
	v_mov_b32_e32 v13, v0
	v_mov_b32_e32 v14, v0
	v_mov_b32_e32 v15, v0
	v_mov_b32_e32 v20, v0
	v_mov_b32_e32 v21, v0
	v_mov_b32_e32 v22, v0
	v_mov_b32_e32 v23, v0
	v_mov_b32_e32 v28, v0
	v_mov_b32_e32 v29, v0
	v_mov_b32_e32 v30, v0
	v_mov_b32_e32 v31, v0
	v_mov_b32_e32 v36, v0
	v_mov_b32_e32 v37, v0
	v_mov_b32_e32 v38, v0
	v_mov_b32_e32 v39, v0
	v_mov_b32_e32 v44, v0
	v_mov_b32_e32 v45, v0
	v_mov_b32_e32 v46, v0
	v_mov_b32_e32 v47, v0
	v_mov_b32_e32 v52, v0
	v_mov_b32_e32 v53, v0
	v_mov_b32_e32 v54, v0
	v_mov_b32_e32 v55, v0
	v_mov_b32_e32 v60, v0
	v_mov_b32_e32 v61, v0
	v_mov_b32_e32 v62, v0
	v_mov_b32_e32 v63, v0
	v_mov_b32_e32 v64, v0
	v_mov_b32_e32 v65, v0
	v_mov_b32_e32 v66, v0
	v_mov_b32_e32 v67, v0
	v_mov_b32_e32 v72, v0
	v_mov_b32_e32 v73, v0
	v_mov_b32_e32 v74, v0
	v_mov_b32_e32 v75, v0
	v_mov_b32_e32 v80, v0
	v_mov_b32_e32 v81, v0
	v_mov_b32_e32 v82, v0
	v_mov_b32_e32 v83, v0
	v_mov_b32_e32 v88, v0
	v_mov_b32_e32 v89, v0
	v_mov_b32_e32 v90, v0
	v_mov_b32_e32 v91, v0
	v_mov_b32_e32 v96, v0
	v_mov_b32_e32 v97, v0
	v_mov_b32_e32 v98, v0
	v_mov_b32_e32 v99, v0
	v_mov_b32_e32 v104, v0
	v_mov_b32_e32 v105, v0
	v_mov_b32_e32 v106, v0
	v_mov_b32_e32 v107, v0
	v_mov_b32_e32 v112, v0
	v_mov_b32_e32 v113, v0
	v_mov_b32_e32 v114, v0
	v_mov_b32_e32 v115, v0
	v_mov_b32_e32 v120, v0
	v_mov_b32_e32 v121, v0
	v_mov_b32_e32 v122, v0
	v_mov_b32_e32 v123, v0
	v_mov_b32_e32 v68, v0
	v_mov_b32_e32 v69, v0
	v_mov_b32_e32 v70, v0
	v_mov_b32_e32 v71, v0
	v_mov_b32_e32 v76, v0
	v_mov_b32_e32 v77, v0
	v_mov_b32_e32 v78, v0
	v_mov_b32_e32 v79, v0
	v_mov_b32_e32 v84, v0
	v_mov_b32_e32 v85, v0
	v_mov_b32_e32 v86, v0
	v_mov_b32_e32 v87, v0
	v_mov_b32_e32 v92, v0
	v_mov_b32_e32 v93, v0
	v_mov_b32_e32 v94, v0
	v_mov_b32_e32 v95, v0
	v_mov_b32_e32 v100, v0
	v_mov_b32_e32 v101, v0
	v_mov_b32_e32 v102, v0
	v_mov_b32_e32 v103, v0
	v_mov_b32_e32 v108, v0
	v_mov_b32_e32 v109, v0
	v_mov_b32_e32 v110, v0
	v_mov_b32_e32 v111, v0
	v_mov_b32_e32 v116, v0
	v_mov_b32_e32 v117, v0
	v_mov_b32_e32 v118, v0
	v_mov_b32_e32 v119, v0
	v_mov_b32_e32 v124, v0
	v_mov_b32_e32 v125, v0
	v_mov_b32_e32 v126, v0
	v_mov_b32_e32 v127, v0
	v_readlane_b32 s100, v255, 40
	s_nop 1
	s_cmp_lg_u32 s100, 0
	s_cbranch_scc1 .Lmut_219

; __device__ __forceinline__ unsigned cvt_pk(float lo, float hi) { f32x2_t v = {lo, hi}; bf16x2_t b = __builtin_convertvector(v, bf16x2_t); return __builtin_bit_cast(unsigned, b); }
; __device__ __forceinline__ float sigmoidf_(float x) { return fast_rcp(1.f + fast_exp2(-x * LOG2E)); }
;     __device__ __forceinline__ void operator()(const f32x4 (&acc)[2][2][4][2], const Unit& u, int wr, int wc, int fr, int fq) const {
;         const int row0 = u.pm * BM + wr * 64 + fr;
;         if (u.pn < n_swi) {
;             const int col0 = u.pn * HALF + wc * 32 + 8 * fq;
; #pragma unroll
;             for (int ai = 0; ai < 2; ++ai)
; #pragma unroll
;                 for (int m = 0; m < 4; ++m) {
;                     const int row = row0 + ai * HALF + m * 16; float a[8];
; #pragma unroll
;                     for (int n = 0; n < 2; ++n)
; #pragma unroll
;                         for (int i = 0; i < 4; ++i) { const float g = acc[ai][0][m][n][i], up = acc[ai][1][m][n][i]; a[n * 4 + i] = g * sigmoidf_(g) * up; }
;                     u32x4 w; w.x = cvt_pk(a[0], a[1]); w.y = cvt_pk(a[2], a[3]); w.z = cvt_pk(a[4], a[5]); w.w = cvt_pk(a[6], a[7]);
;                     *(u32x4*)(ACT + (size_t)row * DFF + col0) = w;
;                 }
.LBB0_222:
	v_readlane_b32 s100, v255, 40
	s_nop 1
	s_cmp_lg_u32 s100, 0
	s_cbranch_scc1 .Lmut_epi
	v_mul_f32_e32 v142, 0xbfb8aa3b, v124
	v_mul_f32_e32 v143, 0xbfb8aa3b, v125
	v_exp_f32_e32 v142, v142
	v_exp_f32_e32 v143, v143
	v_lshl_or_b32 v146, s26, 7, v140
	v_ashrrev_i32_e32 v147, 31, v146
	v_add_f32_e32 v142, 1.0, v142
	v_add_f32_e32 v143, 1.0, v143
	v_rcp_f32_e32 v144, v142
	v_rcp_f32_e32 v145, v143
	v_mul_f32_e32 v143, 0xbfb8aa3b, v126
	v_exp_f32_e32 v143, v143
	v_lshl_add_u32 v142, s27, 8, v138
	v_pk_mul_f32 v[124:125], v[124:125], v[144:145]
	v_mul_f32_e32 v144, 0xbfb8aa3b, v127
	v_exp_f32_e32 v144, v144
	v_pk_mul_f32 v[120:121], v[120:121], v[124:125]
	v_add_f32_e32 v124, 1.0, v143
	v_mul_f32_e32 v143, 0xbfb8aa3b, v116
	v_add_f32_e32 v125, 1.0, v144
	v_rcp_f32_e32 v124, v124
	v_rcp_f32_e32 v125, v125
	v_exp_f32_e32 v143, v143
	v_mul_f32_e32 v144, 0xbfb8aa3b, v117
	v_exp_f32_e32 v144, v144
	v_pk_mul_f32 v[124:125], v[126:127], v[124:125]
	v_add_f32_e32 v126, 1.0, v143
	v_mul_f32_e32 v143, 0xbfb8aa3b, v118
	v_add_f32_e32 v127, 1.0, v144
	v_exp_f32_e32 v143, v143
	v_mul_f32_e32 v144, 0xbfb8aa3b, v119
	v_exp_f32_e32 v145, v144
	v_rcp_f32_e32 v126, v126
	v_add_f32_e32 v143, 1.0, v143
	v_rcp_f32_e32 v127, v127
	v_rcp_f32_e32 v144, v143
	v_add_f32_e32 v143, 1.0, v145
	v_rcp_f32_e32 v145, v143
	v_pk_mul_f32 v[116:117], v[116:117], v[126:127]
	v_pk_mul_f32 v[122:123], v[122:123], v[124:125]
	v_pk_mul_f32 v[112:113], v[112:113], v[116:117]
	v_pk_mul_f32 v[116:117], v[118:119], v[144:145]
	v_cvt_pk_bf16_f32 v118, v112, v113
	v_pk_mul_f32 v[114:115], v[114:115], v[116:117]
	v_cvt_pk_bf16_f32 v117, v122, v123
	v_cvt_pk_bf16_f32 v119, v114, v115
	v_mul_f32_e32 v114, 0xbfb8aa3b, v108
	v_exp_f32_e32 v114, v114
	v_mul_f32_e32 v115, 0xbfb8aa3b, v109
	v_exp_f32_e32 v115, v115
	v_mov_b64_e32 v[112:113], s[60:61]
	v_add_f32_e32 v114, 1.0, v114
	s_movk_i32 s15, 0x2c00
	v_rcp_f32_e32 v122, v114
	v_add_f32_e32 v114, 1.0, v115
	v_cvt_pk_bf16_f32 v116, v120, v121
	v_mad_i64_i32 v[120:121], s[2:3], v142, s15, v[112:113]
	v_rcp_f32_e32 v123, v114
	v_lshlrev_b64 v[114:115], 1, v[146:147]
	v_lshl_add_u64 v[120:121], v[120:121], 0, v[114:115]
	global_store_dwordx4 v[120:121], v[116:119], off
	v_pk_mul_f32 v[108:109], v[108:109], v[122:123]
	s_and_b64 vcc, exec, s[38:39]
	v_mul_f32_e32 v116, 0xbfb8aa3b, v110
	v_mul_f32_e32 v117, 0xbfb8aa3b, v111
	v_exp_f32_e32 v116, v116
	v_exp_f32_e32 v117, v117
	v_pk_mul_f32 v[104:105], v[104:105], v[108:109]
	v_add_f32_e32 v108, 1.0, v116
	v_add_f32_e32 v109, 1.0, v117
	v_mul_f32_e32 v116, 0xbfb8aa3b, v100
	v_mul_f32_e32 v117, 0xbfb8aa3b, v101
	v_rcp_f32_e32 v108, v108
	v_rcp_f32_e32 v109, v109
	v_exp_f32_e32 v116, v116
	v_exp_f32_e32 v117, v117
	v_pk_mul_f32 v[108:109], v[110:111], v[108:109]
	v_add_f32_e32 v110, 1.0, v116
	v_add_f32_e32 v111, 1.0, v117
	v_mul_f32_e32 v116, 0xbfb8aa3b, v102
	v_mul_f32_e32 v117, 0xbfb8aa3b, v103
	v_exp_f32_e32 v116, v116
	v_exp_f32_e32 v117, v117
	v_rcp_f32_e32 v110, v110
	v_rcp_f32_e32 v111, v111
	v_add_f32_e32 v116, 1.0, v116
	v_add_f32_e32 v117, 1.0, v117
	v_rcp_f32_e32 v116, v116
	v_rcp_f32_e32 v117, v117
	v_pk_mul_f32 v[100:101], v[100:101], v[110:111]
	v_pk_mul_f32 v[106:107], v[106:107], v[108:109]
	v_pk_mul_f32 v[100:101], v[96:97], v[100:101]
	v_pk_mul_f32 v[96:97], v[102:103], v[116:117]
	v_or_b32_e32 v108, 16, v142
	v_pk_mul_f32 v[102:103], v[98:99], v[96:97]
	v_mul_f32_e32 v99, 0xbfb8aa3b, v92
	v_cvt_pk_bf16_f32 v98, v100, v101
	v_exp_f32_e32 v100, v99
	v_mul_f32_e32 v99, 0xbfb8aa3b, v93
	v_exp_f32_e32 v101, v99
	v_cvt_pk_bf16_f32 v99, v102, v103
	v_mad_i64_i32 v[102:103], s[2:3], v108, s15, v[112:113]
	v_cvt_pk_bf16_f32 v96, v104, v105
	v_cvt_pk_bf16_f32 v97, v106, v107
	v_add_f32_e32 v100, 1.0, v100
	v_add_f32_e32 v101, 1.0, v101
	v_lshl_add_u64 v[102:103], v[102:103], 0, v[114:115]
	v_rcp_f32_e32 v100, v100
	v_rcp_f32_e32 v101, v101
	global_store_dwordx4 v[102:103], v[96:99], off
	v_pk_mul_f32 v[92:93], v[92:93], v[100:101]
	s_nop 0
	v_mul_f32_e32 v96, 0xbfb8aa3b, v94
	v_mul_f32_e32 v97, 0xbfb8aa3b, v95
	v_exp_f32_e32 v96, v96
	v_exp_f32_e32 v97, v97
	v_pk_mul_f32 v[88:89], v[88:89], v[92:93]
	v_add_f32_e32 v92, 1.0, v96
	v_add_f32_e32 v93, 1.0, v97
	v_mul_f32_e32 v96, 0xbfb8aa3b, v84
	v_mul_f32_e32 v97, 0xbfb8aa3b, v85
	v_rcp_f32_e32 v92, v92
	v_rcp_f32_e32 v93, v93
	v_exp_f32_e32 v96, v96
	v_exp_f32_e32 v97, v97
	v_pk_mul_f32 v[92:93], v[94:95], v[92:93]
	v_add_f32_e32 v94, 1.0, v96
	v_add_f32_e32 v95, 1.0, v97
	v_mul_f32_e32 v96, 0xbfb8aa3b, v86
	v_mul_f32_e32 v97, 0xbfb8aa3b, v87
	v_exp_f32_e32 v96, v96
	v_exp_f32_e32 v97, v97
	v_rcp_f32_e32 v94, v94
	v_rcp_f32_e32 v95, v95
	v_add_f32_e32 v96, 1.0, v96
	v_add_f32_e32 v97, 1.0, v97
	v_rcp_f32_e32 v96, v96
	v_rcp_f32_e32 v97, v97
	v_pk_mul_f32 v[84:85], v[84:85], v[94:95]
	v_pk_mul_f32 v[90:91], v[90:91], v[92:93]
	v_pk_mul_f32 v[84:85], v[80:81], v[84:85]
	v_pk_mul_f32 v[80:81], v[86:87], v[96:97]
	v_or_b32_e32 v92, 32, v142
	v_pk_mul_f32 v[86:87], v[82:83], v[80:81]
	v_mul_f32_e32 v83, 0xbfb8aa3b, v76
	v_cvt_pk_bf16_f32 v82, v84, v85
	v_exp_f32_e32 v84, v83
	v_mul_f32_e32 v83, 0xbfb8aa3b, v77
	v_exp_f32_e32 v85, v83
	v_cvt_pk_bf16_f32 v83, v86, v87
	v_mad_i64_i32 v[86:87], s[2:3], v92, s15, v[112:113]
	v_cvt_pk_bf16_f32 v80, v88, v89
	v_cvt_pk_bf16_f32 v81, v90, v91
	v_add_f32_e32 v84, 1.0, v84
	v_add_f32_e32 v85, 1.0, v85
	v_lshl_add_u64 v[86:87], v[86:87], 0, v[114:115]
	v_rcp_f32_e32 v84, v84
	v_rcp_f32_e32 v85, v85
	global_store_dwordx4 v[86:87], v[80:83], off
	v_pk_mul_f32 v[76:77], v[76:77], v[84:85]
	s_nop 0
	v_mul_f32_e32 v80, 0xbfb8aa3b, v78
	v_mul_f32_e32 v81, 0xbfb8aa3b, v79
	v_exp_f32_e32 v80, v80
; __device__ __forceinline__ unsigned cvt_pk(float lo, float hi) { f32x2_t v = {lo, hi}; bf16x2_t b = __builtin_convertvector(v, bf16x2_t); return __builtin_bit_cast(unsigned, b); }
; __device__ __forceinline__ float sigmoidf_(float x) { return fast_rcp(1.f + fast_exp2(-x * LOG2E)); }
;     __device__ __forceinline__ void operator()(const f32x4 (&acc)[2][2][4][2], const Unit& u, int wr, int wc, int fr, int fq) const {
;         const int row0 = u.pm * BM + wr * 64 + fr;
;         if (u.pn < n_swi) {
;             const int col0 = u.pn * HALF + wc * 32 + 8 * fq;
; #pragma unroll
;             for (int ai = 0; ai < 2; ++ai)
; #pragma unroll
;                 for (int m = 0; m < 4; ++m) {
;                     const int row = row0 + ai * HALF + m * 16; float a[8];
; #pragma unroll
;                     for (int n = 0; n < 2; ++n)
; #pragma unroll
;                         for (int i = 0; i < 4; ++i) { const float g = acc[ai][0][m][n][i], up = acc[ai][1][m][n][i]; a[n * 4 + i] = g * sigmoidf_(g) * up; }
;                     u32x4 w; w.x = cvt_pk(a[0], a[1]); w.y = cvt_pk(a[2], a[3]); w.z = cvt_pk(a[4], a[5]); w.w = cvt_pk(a[6], a[7]);
;                     *(u32x4*)(ACT + (size_t)row * DFF + col0) = w;
;                 }
	v_exp_f32_e32 v81, v81
	v_pk_mul_f32 v[72:73], v[72:73], v[76:77]
	v_add_f32_e32 v76, 1.0, v80
	v_add_f32_e32 v77, 1.0, v81
	v_mul_f32_e32 v80, 0xbfb8aa3b, v68
	v_mul_f32_e32 v81, 0xbfb8aa3b, v69
	v_rcp_f32_e32 v76, v76
	v_rcp_f32_e32 v77, v77
	v_exp_f32_e32 v80, v80
	v_exp_f32_e32 v81, v81
	v_pk_mul_f32 v[76:77], v[78:79], v[76:77]
	v_add_f32_e32 v78, 1.0, v80
	v_add_f32_e32 v79, 1.0, v81
	v_mul_f32_e32 v80, 0xbfb8aa3b, v70
	v_mul_f32_e32 v81, 0xbfb8aa3b, v71
	v_exp_f32_e32 v80, v80
	v_exp_f32_e32 v81, v81
	v_rcp_f32_e32 v78, v78
	v_rcp_f32_e32 v79, v79
	v_add_f32_e32 v80, 1.0, v80
	v_add_f32_e32 v81, 1.0, v81
	v_rcp_f32_e32 v80, v80
	v_rcp_f32_e32 v81, v81
	v_pk_mul_f32 v[68:69], v[68:69], v[78:79]
	v_pk_mul_f32 v[74:75], v[74:75], v[76:77]
	v_pk_mul_f32 v[68:69], v[64:65], v[68:69]
	v_pk_mul_f32 v[64:65], v[70:71], v[80:81]
	v_or_b32_e32 v76, 48, v142
	v_pk_mul_f32 v[70:71], v[66:67], v[64:65]
	v_cvt_pk_bf16_f32 v66, v68, v69
	v_mul_f32_e32 v68, 0xbfb8aa3b, v60
	v_cvt_pk_bf16_f32 v67, v70, v71
	v_exp_f32_e32 v70, v68
	v_mul_f32_e32 v68, 0xbfb8aa3b, v61
	v_exp_f32_e32 v71, v68
	v_mad_i64_i32 v[68:69], s[2:3], v76, s15, v[112:113]
	v_cvt_pk_bf16_f32 v64, v72, v73
	v_cvt_pk_bf16_f32 v65, v74, v75
	v_add_f32_e32 v70, 1.0, v70
	v_add_f32_e32 v71, 1.0, v71
	v_lshl_add_u64 v[68:69], v[68:69], 0, v[114:115]
	v_rcp_f32_e32 v70, v70
	v_rcp_f32_e32 v71, v71
	global_store_dwordx4 v[68:69], v[64:67], off
	v_pk_mul_f32 v[60:61], v[60:61], v[70:71]
	s_nop 0
	v_mul_f32_e32 v64, 0xbfb8aa3b, v62
	v_mul_f32_e32 v65, 0xbfb8aa3b, v63
	v_exp_f32_e32 v64, v64
	v_exp_f32_e32 v65, v65
	v_pk_mul_f32 v[56:57], v[56:57], v[60:61]
	v_add_u32_e32 v66, 0x80, v142
	v_add_f32_e32 v60, 1.0, v64
	v_add_f32_e32 v61, 1.0, v65
	v_mul_f32_e32 v64, 0xbfb8aa3b, v52
	v_mul_f32_e32 v65, 0xbfb8aa3b, v53
	v_rcp_f32_e32 v60, v60
	v_rcp_f32_e32 v61, v61
	v_exp_f32_e32 v64, v64
	v_exp_f32_e32 v65, v65
	v_pk_mul_f32 v[60:61], v[62:63], v[60:61]
	v_add_f32_e32 v62, 1.0, v64
	v_add_f32_e32 v63, 1.0, v65
	v_mul_f32_e32 v64, 0xbfb8aa3b, v54
	v_mul_f32_e32 v65, 0xbfb8aa3b, v55
	v_exp_f32_e32 v64, v64
	v_exp_f32_e32 v65, v65
	v_rcp_f32_e32 v62, v62
	v_rcp_f32_e32 v63, v63
	v_add_f32_e32 v64, 1.0, v64
	v_add_f32_e32 v65, 1.0, v65
	v_rcp_f32_e32 v64, v64
	v_rcp_f32_e32 v65, v65
	v_pk_mul_f32 v[52:53], v[52:53], v[62:63]
	v_pk_mul_f32 v[58:59], v[58:59], v[60:61]
	v_pk_mul_f32 v[52:53], v[48:49], v[52:53]
	v_pk_mul_f32 v[48:49], v[54:55], v[64:65]
	s_nop 0
	v_pk_mul_f32 v[54:55], v[50:51], v[48:49]
	v_mul_f32_e32 v51, 0xbfb8aa3b, v44
	v_cvt_pk_bf16_f32 v50, v52, v53
	v_exp_f32_e32 v52, v51
	v_mul_f32_e32 v51, 0xbfb8aa3b, v45
	v_exp_f32_e32 v53, v51
	v_cvt_pk_bf16_f32 v51, v54, v55
	v_mad_i64_i32 v[54:55], s[2:3], v66, s15, v[112:113]
	v_cvt_pk_bf16_f32 v48, v56, v57
	v_cvt_pk_bf16_f32 v49, v58, v59
	v_add_f32_e32 v52, 1.0, v52
	v_add_f32_e32 v53, 1.0, v53
	v_lshl_add_u64 v[54:55], v[54:55], 0, v[114:115]
	v_rcp_f32_e32 v52, v52
	v_rcp_f32_e32 v53, v53
	global_store_dwordx4 v[54:55], v[48:51], off
	v_pk_mul_f32 v[44:45], v[44:45], v[52:53]
	s_nop 0
	v_mul_f32_e32 v48, 0xbfb8aa3b, v46
	v_mul_f32_e32 v49, 0xbfb8aa3b, v47
	v_exp_f32_e32 v48, v48
	v_exp_f32_e32 v49, v49
	v_pk_mul_f32 v[40:41], v[40:41], v[44:45]
	v_add_f32_e32 v44, 1.0, v48
	v_add_f32_e32 v45, 1.0, v49
	v_mul_f32_e32 v48, 0xbfb8aa3b, v36
	v_mul_f32_e32 v49, 0xbfb8aa3b, v37
	v_rcp_f32_e32 v44, v44
	v_rcp_f32_e32 v45, v45
	v_exp_f32_e32 v48, v48
	v_exp_f32_e32 v49, v49
	v_pk_mul_f32 v[44:45], v[46:47], v[44:45]
	v_add_f32_e32 v46, 1.0, v48
	v_add_f32_e32 v47, 1.0, v49
	v_mul_f32_e32 v48, 0xbfb8aa3b, v38
	v_mul_f32_e32 v49, 0xbfb8aa3b, v39
	v_exp_f32_e32 v48, v48
	v_exp_f32_e32 v49, v49
	v_rcp_f32_e32 v46, v46
	v_rcp_f32_e32 v47, v47
	v_add_f32_e32 v48, 1.0, v48
	v_add_f32_e32 v49, 1.0, v49
	v_rcp_f32_e32 v48, v48
	v_rcp_f32_e32 v49, v49
	v_pk_mul_f32 v[36:37], v[36:37], v[46:47]
; __device__ __forceinline__ unsigned cvt_pk(float lo, float hi) { f32x2_t v = {lo, hi}; bf16x2_t b = __builtin_convertvector(v, bf16x2_t); return __builtin_bit_cast(unsigned, b); }
; __device__ __forceinline__ float sigmoidf_(float x) { return fast_rcp(1.f + fast_exp2(-x * LOG2E)); }
; #define PG8_BAR __builtin_amdgcn_s_barrier()
;     __device__ __forceinline__ void operator()(const f32x4 (&acc)[2][2][4][2], const Unit& u, int wr, int wc, int fr, int fq) const {
;         const int row0 = u.pm * BM + wr * 64 + fr;
;         if (u.pn < n_swi) {
;             const int col0 = u.pn * HALF + wc * 32 + 8 * fq;
; #pragma unroll
;             for (int ai = 0; ai < 2; ++ai)
; #pragma unroll
;                 for (int m = 0; m < 4; ++m) {
;                     const int row = row0 + ai * HALF + m * 16; float a[8];
; #pragma unroll
;                     for (int n = 0; n < 2; ++n)
; #pragma unroll
;                         for (int i = 0; i < 4; ++i) { const float g = acc[ai][0][m][n][i], up = acc[ai][1][m][n][i]; a[n * 4 + i] = g * sigmoidf_(g) * up; }
;                     u32x4 w; w.x = cvt_pk(a[0], a[1]); w.y = cvt_pk(a[2], a[3]); w.z = cvt_pk(a[4], a[5]); w.w = cvt_pk(a[6], a[7]);
;                     *(u32x4*)(ACT + (size_t)row * DFF + col0) = w;
;                 }
; template <class Epi, bool ALIGN_EPI = PG8_ALIGN>
; __device__ __forceinline__ void gemm_phase(LAS unsigned char* lds, const Gemm g, const StaticOrder& S, const Epi& E) {
;     ...
;         if (ALIGN_EPI) { if (wr == 0) PG8_BAR; }
;         E(acc, cur, wr, wc, fr, fq);
;         if (!has_next) break;
; #pragma unroll
;         for (int a = 0; a < 2; ++a)
; #pragma unroll
;             for (int b = 0; b < 2; ++b)
; #pragma unroll
;                 for (int m = 0; m < 4; ++m)
; #pragma unroll
;                     for (int n = 0; n < 2; ++n) acc[a][b][m][n] = (f32x4){0.f, 0.f, 0.f, 0.f};
;         cur = nxt; cA = nA; cB = nB; ++ui;
;         if (ALIGN_EPI) { if (wr == 1) PG8_BAR; }
	v_pk_mul_f32 v[42:43], v[42:43], v[44:45]
	v_pk_mul_f32 v[36:37], v[32:33], v[36:37]
	v_pk_mul_f32 v[32:33], v[38:39], v[48:49]
	v_add_u32_e32 v44, 0x90, v142
	v_pk_mul_f32 v[38:39], v[34:35], v[32:33]
	v_mul_f32_e32 v35, 0xbfb8aa3b, v28
	v_cvt_pk_bf16_f32 v34, v36, v37
	v_exp_f32_e32 v36, v35
	v_mul_f32_e32 v35, 0xbfb8aa3b, v29
	v_exp_f32_e32 v37, v35
	v_cvt_pk_bf16_f32 v35, v38, v39
	v_mad_i64_i32 v[38:39], s[2:3], v44, s15, v[112:113]
	v_cvt_pk_bf16_f32 v32, v40, v41
	v_cvt_pk_bf16_f32 v33, v42, v43
	v_add_f32_e32 v36, 1.0, v36
	v_add_f32_e32 v37, 1.0, v37
	v_lshl_add_u64 v[38:39], v[38:39], 0, v[114:115]
	v_rcp_f32_e32 v36, v36
	v_rcp_f32_e32 v37, v37
	global_store_dwordx4 v[38:39], v[32:35], off
	v_pk_mul_f32 v[28:29], v[28:29], v[36:37]
	s_nop 0
	v_mul_f32_e32 v32, 0xbfb8aa3b, v30
	v_mul_f32_e32 v33, 0xbfb8aa3b, v31
	v_exp_f32_e32 v32, v32
	v_exp_f32_e32 v33, v33
	v_pk_mul_f32 v[24:25], v[24:25], v[28:29]
	v_add_f32_e32 v28, 1.0, v32
	v_add_f32_e32 v29, 1.0, v33
	v_mul_f32_e32 v32, 0xbfb8aa3b, v20
	v_mul_f32_e32 v33, 0xbfb8aa3b, v21
	v_rcp_f32_e32 v28, v28
	v_rcp_f32_e32 v29, v29
	v_exp_f32_e32 v32, v32
	v_exp_f32_e32 v33, v33
	v_pk_mul_f32 v[28:29], v[30:31], v[28:29]
	v_add_f32_e32 v30, 1.0, v32
	v_add_f32_e32 v31, 1.0, v33
	v_mul_f32_e32 v32, 0xbfb8aa3b, v22
	v_mul_f32_e32 v33, 0xbfb8aa3b, v23
	v_exp_f32_e32 v32, v32
	v_exp_f32_e32 v33, v33
	v_rcp_f32_e32 v30, v30
	v_rcp_f32_e32 v31, v31
	v_add_f32_e32 v32, 1.0, v32
	v_add_f32_e32 v33, 1.0, v33
	v_rcp_f32_e32 v32, v32
	v_rcp_f32_e32 v33, v33
	v_pk_mul_f32 v[20:21], v[20:21], v[30:31]
	v_pk_mul_f32 v[26:27], v[26:27], v[28:29]
	v_pk_mul_f32 v[20:21], v[16:17], v[20:21]
	v_pk_mul_f32 v[16:17], v[22:23], v[32:33]
	v_add_u32_e32 v28, 0xa0, v142
	v_pk_mul_f32 v[22:23], v[18:19], v[16:17]
	v_mul_f32_e32 v19, 0xbfb8aa3b, v12
	v_cvt_pk_bf16_f32 v18, v20, v21
	v_exp_f32_e32 v20, v19
	v_mul_f32_e32 v19, 0xbfb8aa3b, v13
	v_exp_f32_e32 v21, v19
	v_cvt_pk_bf16_f32 v19, v22, v23
	v_mad_i64_i32 v[22:23], s[2:3], v28, s15, v[112:113]
	v_cvt_pk_bf16_f32 v16, v24, v25
	v_cvt_pk_bf16_f32 v17, v26, v27
	v_add_f32_e32 v20, 1.0, v20
	v_add_f32_e32 v21, 1.0, v21
	v_lshl_add_u64 v[22:23], v[22:23], 0, v[114:115]
	v_rcp_f32_e32 v20, v20
	v_rcp_f32_e32 v21, v21
	global_store_dwordx4 v[22:23], v[16:19], off
	v_pk_mul_f32 v[12:13], v[12:13], v[20:21]
	s_nop 0
	v_mul_f32_e32 v16, 0xbfb8aa3b, v14
	v_mul_f32_e32 v17, 0xbfb8aa3b, v15
	v_exp_f32_e32 v16, v16
	v_exp_f32_e32 v17, v17
	v_pk_mul_f32 v[8:9], v[8:9], v[12:13]
	v_add_f32_e32 v12, 1.0, v16
	v_add_f32_e32 v13, 1.0, v17
	v_mul_f32_e32 v16, 0xbfb8aa3b, v4
	v_mul_f32_e32 v17, 0xbfb8aa3b, v5
	v_rcp_f32_e32 v12, v12
	v_rcp_f32_e32 v13, v13
	v_exp_f32_e32 v16, v16
	v_exp_f32_e32 v17, v17
	v_pk_mul_f32 v[12:13], v[14:15], v[12:13]
	v_add_f32_e32 v14, 1.0, v16
	v_add_f32_e32 v15, 1.0, v17
	v_mul_f32_e32 v16, 0xbfb8aa3b, v6
	v_mul_f32_e32 v17, 0xbfb8aa3b, v7
	v_exp_f32_e32 v16, v16
	v_exp_f32_e32 v17, v17
	v_rcp_f32_e32 v14, v14
	v_rcp_f32_e32 v15, v15
	v_add_f32_e32 v16, 1.0, v16
	v_add_f32_e32 v17, 1.0, v17
	v_rcp_f32_e32 v16, v16
	v_rcp_f32_e32 v17, v17
	v_pk_mul_f32 v[4:5], v[4:5], v[14:15]
	v_pk_mul_f32 v[10:11], v[10:11], v[12:13]
	v_pk_mul_f32 v[4:5], v[0:1], v[4:5]
	v_pk_mul_f32 v[0:1], v[6:7], v[16:17]
	v_add_u32_e32 v12, 0xb0, v142
	v_pk_mul_f32 v[6:7], v[2:3], v[0:1]
	v_cvt_pk_bf16_f32 v2, v4, v5
	v_mad_i64_i32 v[4:5], s[2:3], v12, s15, v[112:113]
	v_cvt_pk_bf16_f32 v0, v8, v9
	v_cvt_pk_bf16_f32 v1, v10, v11
	v_cvt_pk_bf16_f32 v3, v6, v7
	v_lshl_add_u64 v[4:5], v[4:5], 0, v[114:115]
	s_mov_b64 s[2:3], -1
	global_store_dwordx4 v[4:5], v[0:3], off
	s_cbranch_vccnz .LBB0_212
.Lepi_after:
	s_andn2_b64 vcc, exec, s[8:9]
	s_cbranch_vccnz .LBB0_211
	s_barrier
	s_branch .LBB0_211
.Lmut_219:
	s_branch .LBB0_220
.Lmut_epi:
	s_movk_i32 s15, 0x2c00
	s_and_b64 vcc, exec, s[38:39]
	s_mov_b64 s[2:3], -1
	s_cbranch_vccnz .LBB0_212
	s_branch .Lepi_after

; __device__ __forceinline__ unsigned cvt_pk(float lo, float hi) { f32x2_t v = {lo, hi}; bf16x2_t b = __builtin_convertvector(v, bf16x2_t); return __builtin_bit_cast(unsigned, b); }
;     __device__ __forceinline__ void operator()(const f32x4 (&acc)[2][2][4][2], const Unit& u, int wr, int wc, int fr, int fq) const {
;         const int row0 = u.pm * BM + wr * 64 + fr, col0 = u.pn * BM + wc * 32 + 8 * fq;
;         float scv[2][4];
; #pragma unroll
;         for (int ai = 0; ai < 2; ++ai)
; #pragma unroll
;             for (int m = 0; m < 4; ++m) scv[ai][m] = rs ? rs[(size_t)(row0 + ai * HALF + m * 16) * rs_stride] * cs : cs;
; #pragma unroll
;         for (int ai = 0; ai < 2; ++ai)
; #pragma unroll
;             for (int m = 0; m < 4; ++m) {
;                 const int row = row0 + ai * HALF + m * 16; const float sc = scv[ai][m];
;                 bf16_t* rowp = O + (size_t)row * ldc + col0;
; #pragma unroll
;                 for (int bj = 0; bj < 2; ++bj) { const f32x4 v0 = acc[ai][bj][m][0] * sc, v1 = acc[ai][bj][m][1] * sc;
;                     u32x4 w; w.x = cvt_pk(v0[0], v0[1]); w.y = cvt_pk(v0[2], v0[3]); w.z = cvt_pk(v1[0], v1[1]); w.w = cvt_pk(v1[2], v1[3]);
;                     *(u32x4*)(rowp + bj * HALF) = w; }
;             }
;     }
.LBB0_666:
	v_lshl_add_u32 v158, s27, 8, v139
	v_readlane_b32 s20, v253, 39
	v_ashrrev_i32_e32 v159, 31, v158
	v_readlane_b32 s21, v253, 40
	v_or_b32_e32 v168, 16, v158
	v_ashrrev_i32_e32 v169, 31, v168
	v_lshl_add_u64 v[140:141], v[158:159], 3, s[20:21]
	global_load_dword v170, v[140:141], off
	v_lshl_add_u64 v[140:141], v[168:169], 3, s[20:21]
	global_load_dword v166, v[140:141], off
	v_or_b32_e32 v164, 32, v158
	v_ashrrev_i32_e32 v165, 31, v164
	v_lshl_add_u64 v[140:141], v[164:165], 3, s[20:21]
	global_load_dword v162, v[140:141], off
	v_or_b32_e32 v160, 48, v158
	v_ashrrev_i32_e32 v161, 31, v160
	v_lshl_add_u64 v[140:141], v[160:161], 3, s[20:21]
	global_load_dword v156, v[140:141], off
	v_add_u32_e32 v154, 0x80, v158
	v_ashrrev_i32_e32 v155, 31, v154
	v_lshl_add_u64 v[140:141], v[154:155], 3, s[20:21]
	global_load_dword v150, v[140:141], off
	v_add_u32_e32 v148, 0x90, v158
	v_ashrrev_i32_e32 v149, 31, v148
	v_lshl_add_u64 v[140:141], v[148:149], 3, s[20:21]
	global_load_dword v146, v[140:141], off
	v_add_u32_e32 v144, 0xa0, v158
	v_ashrrev_i32_e32 v145, 31, v144
	v_lshl_add_u64 v[140:141], v[144:145], 3, s[20:21]
	global_load_dword v142, v[140:141], off
	v_add_u32_e32 v140, 0xb0, v158
	v_ashrrev_i32_e32 v141, 31, v140
	v_lshl_add_u64 v[152:153], v[140:141], 3, s[20:21]
	global_load_dword v138, v[152:153], off
	v_readlane_b32 s20, v253, 45
	v_lshl_or_b32 v172, s26, 8, v147
	v_readlane_b32 s21, v253, 46
	v_ashrrev_i32_e32 v173, 31, v172
	s_and_b64 vcc, exec, s[42:43]
	v_mov_b64_e32 v[152:153], s[20:21]
	s_movk_i32 s20, 0x600
	v_mad_i64_i32 v[174:175], s[24:25], v158, s20, v[152:153]
	v_lshlrev_b64 v[158:159], 1, v[172:173]
	v_lshl_add_u64 v[172:173], v[174:175], 0, v[158:159]
	s_waitcnt vmcnt(0)
	v_pk_mul_f32 v[122:123], v[122:123], v[170:171] op_sel_hi:[1,0]
	v_pk_mul_f32 v[120:121], v[120:121], v[170:171] op_sel_hi:[1,0]
	v_pk_mul_f32 v[126:127], v[126:127], v[170:171] op_sel_hi:[1,0]
	v_pk_mul_f32 v[124:125], v[124:125], v[170:171] op_sel_hi:[1,0]
	v_cvt_pk_bf16_f32 v120, v120, v121
	v_cvt_pk_bf16_f32 v121, v122, v123
	v_cvt_pk_bf16_f32 v122, v124, v125
	v_cvt_pk_bf16_f32 v123, v126, v127
	global_store_dwordx4 v[172:173], v[120:123], off
	v_pk_mul_f32 v[118:119], v[118:119], v[170:171] op_sel_hi:[1,0]
	v_pk_mul_f32 v[116:117], v[116:117], v[170:171] op_sel_hi:[1,0]
	v_pk_mul_f32 v[120:121], v[114:115], v[170:171] op_sel_hi:[1,0]
	v_pk_mul_f32 v[114:115], v[112:113], v[170:171] op_sel_hi:[1,0]
	v_cvt_pk_bf16_f32 v112, v116, v117
	v_cvt_pk_bf16_f32 v113, v118, v119
	v_cvt_pk_bf16_f32 v114, v114, v115
	v_cvt_pk_bf16_f32 v115, v120, v121
	global_store_dwordx4 v[172:173], v[112:115], off offset:256
	v_pk_mul_f32 v[110:111], v[110:111], v[166:167] op_sel_hi:[1,0]
	v_pk_mul_f32 v[108:109], v[108:109], v[166:167] op_sel_hi:[1,0]
	v_mad_i64_i32 v[112:113], s[24:25], v168, s20, v[152:153]
	v_pk_mul_f32 v[114:115], v[106:107], v[166:167] op_sel_hi:[1,0]
	v_pk_mul_f32 v[106:107], v[104:105], v[166:167] op_sel_hi:[1,0]
	v_lshl_add_u64 v[112:113], v[112:113], 0, v[158:159]
	v_cvt_pk_bf16_f32 v104, v108, v109
	v_cvt_pk_bf16_f32 v105, v110, v111
	v_cvt_pk_bf16_f32 v106, v106, v107
	v_cvt_pk_bf16_f32 v107, v114, v115
	global_store_dwordx4 v[112:113], v[104:107], off
	v_pk_mul_f32 v[102:103], v[102:103], v[166:167] op_sel_hi:[1,0]
	v_pk_mul_f32 v[100:101], v[100:101], v[166:167] op_sel_hi:[1,0]
	v_pk_mul_f32 v[104:105], v[98:99], v[166:167] op_sel_hi:[1,0]
	v_pk_mul_f32 v[98:99], v[96:97], v[166:167] op_sel_hi:[1,0]
	v_cvt_pk_bf16_f32 v96, v100, v101
	v_cvt_pk_bf16_f32 v97, v102, v103
	v_cvt_pk_bf16_f32 v98, v98, v99
	v_cvt_pk_bf16_f32 v99, v104, v105
	global_store_dwordx4 v[112:113], v[96:99], off offset:256
	v_pk_mul_f32 v[94:95], v[94:95], v[162:163] op_sel_hi:[1,0]
	v_pk_mul_f32 v[92:93], v[92:93], v[162:163] op_sel_hi:[1,0]
	v_mad_i64_i32 v[96:97], s[24:25], v164, s20, v[152:153]
	v_pk_mul_f32 v[98:99], v[90:91], v[162:163] op_sel_hi:[1,0]
	v_pk_mul_f32 v[90:91], v[88:89], v[162:163] op_sel_hi:[1,0]
	v_lshl_add_u64 v[96:97], v[96:97], 0, v[158:159]
	v_cvt_pk_bf16_f32 v88, v92, v93
	v_cvt_pk_bf16_f32 v89, v94, v95
	v_cvt_pk_bf16_f32 v90, v90, v91
	v_cvt_pk_bf16_f32 v91, v98, v99
	global_store_dwordx4 v[96:97], v[88:91], off
	v_pk_mul_f32 v[86:87], v[86:87], v[162:163] op_sel_hi:[1,0]
	v_pk_mul_f32 v[84:85], v[84:85], v[162:163] op_sel_hi:[1,0]
	v_pk_mul_f32 v[88:89], v[82:83], v[162:163] op_sel_hi:[1,0]
	v_pk_mul_f32 v[82:83], v[80:81], v[162:163] op_sel_hi:[1,0]
	v_cvt_pk_bf16_f32 v80, v84, v85
	v_cvt_pk_bf16_f32 v81, v86, v87
	v_cvt_pk_bf16_f32 v82, v82, v83
	v_cvt_pk_bf16_f32 v83, v88, v89
	global_store_dwordx4 v[96:97], v[80:83], off offset:256
	v_pk_mul_f32 v[78:79], v[78:79], v[156:157] op_sel_hi:[1,0]
	v_pk_mul_f32 v[76:77], v[76:77], v[156:157] op_sel_hi:[1,0]
	v_mad_i64_i32 v[80:81], s[24:25], v160, s20, v[152:153]
; __device__ __forceinline__ unsigned cvt_pk(float lo, float hi) { f32x2_t v = {lo, hi}; bf16x2_t b = __builtin_convertvector(v, bf16x2_t); return __builtin_bit_cast(unsigned, b); }
; #define PG8_BAR __builtin_amdgcn_s_barrier()
;     __device__ __forceinline__ void operator()(const f32x4 (&acc)[2][2][4][2], const Unit& u, int wr, int wc, int fr, int fq) const {
;         const int row0 = u.pm * BM + wr * 64 + fr, col0 = u.pn * BM + wc * 32 + 8 * fq;
;         float scv[2][4];
; #pragma unroll
;         for (int ai = 0; ai < 2; ++ai)
; #pragma unroll
;             for (int m = 0; m < 4; ++m) scv[ai][m] = rs ? rs[(size_t)(row0 + ai * HALF + m * 16) * rs_stride] * cs : cs;
; #pragma unroll
;         for (int ai = 0; ai < 2; ++ai)
; #pragma unroll
;             for (int m = 0; m < 4; ++m) {
;                 const int row = row0 + ai * HALF + m * 16; const float sc = scv[ai][m];
;                 bf16_t* rowp = O + (size_t)row * ldc + col0;
; #pragma unroll
;                 for (int bj = 0; bj < 2; ++bj) { const f32x4 v0 = acc[ai][bj][m][0] * sc, v1 = acc[ai][bj][m][1] * sc;
;                     u32x4 w; w.x = cvt_pk(v0[0], v0[1]); w.y = cvt_pk(v0[2], v0[3]); w.z = cvt_pk(v1[0], v1[1]); w.w = cvt_pk(v1[2], v1[3]);
;                     *(u32x4*)(rowp + bj * HALF) = w; }
;             }
;     }
; template <class Epi, bool ALIGN_EPI = PG8_ALIGN>
; __device__ __forceinline__ void gemm_phase(LAS unsigned char* lds, const Gemm g, const StaticOrder& S, const Epi& E) {
;     ...
;         if (ALIGN_EPI) { if (wr == 0) PG8_BAR; }
;         E(acc, cur, wr, wc, fr, fq);
;         if (!has_next) break;
; #pragma unroll
;         for (int a = 0; a < 2; ++a)
; #pragma unroll
;             for (int b = 0; b < 2; ++b)
; #pragma unroll
;                 for (int m = 0; m < 4; ++m)
; #pragma unroll
;                     for (int n = 0; n < 2; ++n) acc[a][b][m][n] = (f32x4){0.f, 0.f, 0.f, 0.f};
;         cur = nxt; cA = nA; cB = nB; ++ui;
;         if (ALIGN_EPI) { if (wr == 1) PG8_BAR; }
;     }
	v_pk_mul_f32 v[82:83], v[74:75], v[156:157] op_sel_hi:[1,0]
	v_pk_mul_f32 v[74:75], v[72:73], v[156:157] op_sel_hi:[1,0]
	v_lshl_add_u64 v[80:81], v[80:81], 0, v[158:159]
	v_cvt_pk_bf16_f32 v72, v76, v77
	v_cvt_pk_bf16_f32 v73, v78, v79
	v_cvt_pk_bf16_f32 v74, v74, v75
	v_cvt_pk_bf16_f32 v75, v82, v83
	global_store_dwordx4 v[80:81], v[72:75], off
	v_pk_mul_f32 v[70:71], v[70:71], v[156:157] op_sel_hi:[1,0]
	v_pk_mul_f32 v[68:69], v[68:69], v[156:157] op_sel_hi:[1,0]
	v_pk_mul_f32 v[72:73], v[66:67], v[156:157] op_sel_hi:[1,0]
	v_pk_mul_f32 v[66:67], v[64:65], v[156:157] op_sel_hi:[1,0]
	v_cvt_pk_bf16_f32 v64, v68, v69
	v_cvt_pk_bf16_f32 v65, v70, v71
	v_cvt_pk_bf16_f32 v66, v66, v67
	v_cvt_pk_bf16_f32 v67, v72, v73
	global_store_dwordx4 v[80:81], v[64:67], off offset:256
	v_pk_mul_f32 v[62:63], v[62:63], v[150:151] op_sel_hi:[1,0]
	v_pk_mul_f32 v[60:61], v[60:61], v[150:151] op_sel_hi:[1,0]
	v_mad_i64_i32 v[64:65], s[24:25], v154, s20, v[152:153]
	v_pk_mul_f32 v[66:67], v[58:59], v[150:151] op_sel_hi:[1,0]
	v_pk_mul_f32 v[58:59], v[56:57], v[150:151] op_sel_hi:[1,0]
	v_lshl_add_u64 v[64:65], v[64:65], 0, v[158:159]
	v_cvt_pk_bf16_f32 v56, v60, v61
	v_cvt_pk_bf16_f32 v57, v62, v63
	v_cvt_pk_bf16_f32 v58, v58, v59
	v_cvt_pk_bf16_f32 v59, v66, v67
	global_store_dwordx4 v[64:65], v[56:59], off
	v_pk_mul_f32 v[54:55], v[54:55], v[150:151] op_sel_hi:[1,0]
	v_pk_mul_f32 v[52:53], v[52:53], v[150:151] op_sel_hi:[1,0]
	v_pk_mul_f32 v[56:57], v[50:51], v[150:151] op_sel_hi:[1,0]
	v_pk_mul_f32 v[50:51], v[48:49], v[150:151] op_sel_hi:[1,0]
	v_cvt_pk_bf16_f32 v48, v52, v53
	v_cvt_pk_bf16_f32 v49, v54, v55
	v_cvt_pk_bf16_f32 v50, v50, v51
	v_cvt_pk_bf16_f32 v51, v56, v57
	global_store_dwordx4 v[64:65], v[48:51], off offset:256
	v_pk_mul_f32 v[46:47], v[46:47], v[146:147] op_sel_hi:[1,0]
	v_pk_mul_f32 v[44:45], v[44:45], v[146:147] op_sel_hi:[1,0]
	v_mad_i64_i32 v[48:49], s[24:25], v148, s20, v[152:153]
	v_pk_mul_f32 v[50:51], v[42:43], v[146:147] op_sel_hi:[1,0]
	v_pk_mul_f32 v[42:43], v[40:41], v[146:147] op_sel_hi:[1,0]
	v_lshl_add_u64 v[48:49], v[48:49], 0, v[158:159]
	v_cvt_pk_bf16_f32 v40, v44, v45
	v_cvt_pk_bf16_f32 v41, v46, v47
	v_cvt_pk_bf16_f32 v42, v42, v43
	v_cvt_pk_bf16_f32 v43, v50, v51
	global_store_dwordx4 v[48:49], v[40:43], off
	v_pk_mul_f32 v[38:39], v[38:39], v[146:147] op_sel_hi:[1,0]
	v_pk_mul_f32 v[36:37], v[36:37], v[146:147] op_sel_hi:[1,0]
	v_pk_mul_f32 v[40:41], v[34:35], v[146:147] op_sel_hi:[1,0]
	v_pk_mul_f32 v[34:35], v[32:33], v[146:147] op_sel_hi:[1,0]
	v_cvt_pk_bf16_f32 v32, v36, v37
	v_cvt_pk_bf16_f32 v33, v38, v39
	v_cvt_pk_bf16_f32 v34, v34, v35
	v_cvt_pk_bf16_f32 v35, v40, v41
	global_store_dwordx4 v[48:49], v[32:35], off offset:256
	v_pk_mul_f32 v[30:31], v[30:31], v[142:143] op_sel_hi:[1,0]
	v_pk_mul_f32 v[28:29], v[28:29], v[142:143] op_sel_hi:[1,0]
	v_mad_i64_i32 v[32:33], s[24:25], v144, s20, v[152:153]
	v_pk_mul_f32 v[34:35], v[26:27], v[142:143] op_sel_hi:[1,0]
	v_pk_mul_f32 v[26:27], v[24:25], v[142:143] op_sel_hi:[1,0]
	v_lshl_add_u64 v[32:33], v[32:33], 0, v[158:159]
	v_cvt_pk_bf16_f32 v24, v28, v29
	v_cvt_pk_bf16_f32 v25, v30, v31
	v_cvt_pk_bf16_f32 v26, v26, v27
	v_cvt_pk_bf16_f32 v27, v34, v35
	global_store_dwordx4 v[32:33], v[24:27], off
	v_pk_mul_f32 v[22:23], v[22:23], v[142:143] op_sel_hi:[1,0]
	v_pk_mul_f32 v[20:21], v[20:21], v[142:143] op_sel_hi:[1,0]
	v_pk_mul_f32 v[24:25], v[18:19], v[142:143] op_sel_hi:[1,0]
	v_pk_mul_f32 v[18:19], v[16:17], v[142:143] op_sel_hi:[1,0]
	v_cvt_pk_bf16_f32 v16, v20, v21
	v_cvt_pk_bf16_f32 v17, v22, v23
	v_cvt_pk_bf16_f32 v18, v18, v19
	v_cvt_pk_bf16_f32 v19, v24, v25
	global_store_dwordx4 v[32:33], v[16:19], off offset:256
	v_pk_mul_f32 v[14:15], v[14:15], v[138:139] op_sel_hi:[1,0]
	v_pk_mul_f32 v[12:13], v[12:13], v[138:139] op_sel_hi:[1,0]
	v_mad_i64_i32 v[16:17], s[24:25], v140, s20, v[152:153]
	v_pk_mul_f32 v[18:19], v[10:11], v[138:139] op_sel_hi:[1,0]
	v_pk_mul_f32 v[10:11], v[8:9], v[138:139] op_sel_hi:[1,0]
	v_lshl_add_u64 v[16:17], v[16:17], 0, v[158:159]
	v_cvt_pk_bf16_f32 v8, v12, v13
	v_cvt_pk_bf16_f32 v9, v14, v15
	v_cvt_pk_bf16_f32 v10, v10, v11
	v_cvt_pk_bf16_f32 v11, v18, v19
	global_store_dwordx4 v[16:17], v[8:11], off
	v_pk_mul_f32 v[6:7], v[6:7], v[138:139] op_sel_hi:[1,0]
	v_pk_mul_f32 v[4:5], v[4:5], v[138:139] op_sel_hi:[1,0]
	v_pk_mul_f32 v[8:9], v[2:3], v[138:139] op_sel_hi:[1,0]
	v_pk_mul_f32 v[2:3], v[0:1], v[138:139] op_sel_hi:[1,0]
	v_cvt_pk_bf16_f32 v0, v4, v5
	v_cvt_pk_bf16_f32 v1, v6, v7
	v_cvt_pk_bf16_f32 v2, v2, v3
	v_cvt_pk_bf16_f32 v3, v8, v9
	s_mov_b64 s[24:25], -1
	global_store_dwordx4 v[16:17], v[0:3], off offset:256
	s_cbranch_vccnz .LBB0_654
	s_andn2_b64 vcc, exec, s[10:11]
	s_cbranch_vccnz .LBB0_653
	s_barrier
	s_branch .LBB0_653
.Lprobe_tramp:
	s_branch .Lprobe_reenter
.LBB0_669:
	s_waitcnt vmcnt(0)
	s_barrier

; #define LAS __attribute__((address_space(3)))
; template <int PHM, int MIXM>
; __global__ void __launch_bounds__(512, 2) mega(Args Aval) {
;     ...
;     unsigned char* ws = A->ws;
;     float* XF = A->out; bf16_t* XB = (bf16_t*)(ws + WS_XB);
;     const int lo = A->ph_lo, hi = A->ph_hi;
;     cg::grid_group grid = cg::this_grid();
;     __shared__ int s_item;
;     __shared__ unsigned s_bar[2];
;     if (threadIdx.x < 2) s_bar[threadIdx.x] = 0u;
;     __syncthreads();
;     XcdBarrier xbar; xbar.bar = (unsigned*)(ws + WS_CTL) + 2048; xbar.x = 0; xbar.st = nullptr;
;     if (hi - lo > 1) xbar = xcd_barrier_post((unsigned*)(ws + WS_CTL) + 2048, (volatile LAS unsigned*)s_bar);
.LBB0_1250:
	s_mov_b64 exec, -1
	s_nop 1
	v_readlane_b32 s100, v255, 40
	s_nop 1
	s_cmp_ge_u32 s100, 8
	s_cbranch_scc1 .Lprobe_done
	s_add_u32 s100, s100, 1
	s_nop 0
	v_writelane_b32 v255, s100, 40
	s_mov_b32 s100, 1
	s_nop 0
	v_writelane_b32 v252, s100, 0
	s_mov_b32 s100, 2
	s_nop 0
	v_writelane_b32 v252, s100, 1
	v_readlane_b32 s18, v252, 2
	v_readlane_b32 s19, v252, 3
	v_readlane_b32 s74, v255, 41
	v_readlane_b32 s68, v255, 42
	s_nop 1
	s_load_dwordx4 s[28:31], s[18:19], 0x140
	s_load_dwordx2 s[76:77], s[18:19], 0x158
	s_load_dword s33, s[18:19], 0x160
	s_waitcnt vmcnt(0) lgkmcnt(0)
	s_add_u32 s0, s30, 0x2000
	s_addc_u32 s1, s31, 0
	s_barrier
	s_branch .Lprobe_tramp
